# adds the P1 K-loop back-edge rotation (head SALU moved into the fourth load segment) on top of the RSL-cached version; loop body label aligned to 256 B
# baseline (speedup 1.0000x reference)
.LBB0_170:
	s_add_u32 s10, s8, 0xfffc0080
	s_addc_u32 s11, s9, -1
	s_add_i32 s30, 0, 0x10000
	s_cmp_eq_u32 s29, 12
	s_cselect_b32 s13, s3, s11
	s_cselect_b32 s12, s24, s10
	s_cselect_b32 s11, s25, s28
	s_cselect_b32 s10, s26, s27
	s_add_i32 s31, 0, 0x14000
	.p2align	8
.Lk1_body:
	v_add_u32_e32 v0, s30, v197
	ds_read_b128 v[130:133], v0
	ds_read_b128 v[134:137], v0 offset:1024
	ds_read_b128 v[138:141], v0 offset:2048
	ds_read_b128 v[142:145], v0 offset:3072
	v_add_u32_e32 v0, s31, v197
	ds_read_b128 v[170:173], v0
	ds_read_b128 v[174:177], v0 offset:1024
	ds_read_b128 v[202:205], v0 offset:2048
	ds_read_b128 v[206:209], v0 offset:3072
	s_add_i32 m0, s59, 0xc000
	ds_read_b128 v[210:213], v200
	ds_read_b128 v[216:219], v200 offset:1024
	ds_read_b128 v[220:223], v200 offset:2048
	ds_read_b128 v[224:227], v200 offset:3072
	ds_read_b128 v[228:231], v200 offset:4096
	ds_read_b128 v[232:235], v200 offset:5120
	ds_read_b128 v[236:239], v200 offset:6144
	ds_read_b128 v[240:243], v200 offset:7168
	global_load_lds_dwordx4 v166, s[8:9]
	s_add_i32 m0, s59, 0xe000
	s_nop 0
	global_load_lds_dwordx4 v168, s[8:9]
	s_waitcnt vmcnt(8)
	s_waitcnt lgkmcnt(0)
	s_barrier
	s_setprio 1
	s_waitcnt lgkmcnt(0)
	v_mfma_f32_16x16x32_bf16 v[126:129], v[130:133], v[210:213], v[126:129]
	v_mfma_f32_16x16x32_bf16 v[122:125], v[138:141], v[210:213], v[122:125]
	v_mfma_f32_16x16x32_bf16 v[110:113], v[130:133], v[220:223], v[110:113]
	v_mfma_f32_16x16x32_bf16 v[106:109], v[138:141], v[220:223], v[106:109]
	v_mfma_f32_16x16x32_bf16 v[94:97], v[130:133], v[228:231], v[94:97]
	v_mfma_f32_16x16x32_bf16 v[90:93], v[138:141], v[228:231], v[90:93]
	v_mfma_f32_16x16x32_bf16 v[78:81], v[130:133], v[236:239], v[78:81]
	v_mfma_f32_16x16x32_bf16 v[74:77], v[138:141], v[236:239], v[74:77]
	v_mfma_f32_16x16x32_bf16 v[126:129], v[134:137], v[216:219], v[126:129]
	v_mfma_f32_16x16x32_bf16 v[122:125], v[142:145], v[216:219], v[122:125]
	v_mfma_f32_16x16x32_bf16 v[110:113], v[134:137], v[224:227], v[110:113]
	v_mfma_f32_16x16x32_bf16 v[106:109], v[142:145], v[224:227], v[106:109]
	v_mfma_f32_16x16x32_bf16 v[94:97], v[134:137], v[232:235], v[94:97]
	v_mfma_f32_16x16x32_bf16 v[90:93], v[142:145], v[232:235], v[90:93]
	v_mfma_f32_16x16x32_bf16 v[78:81], v[134:137], v[240:243], v[78:81]
	v_mfma_f32_16x16x32_bf16 v[74:77], v[142:145], v[240:243], v[74:77]
	s_setprio 0
	s_setprio 1
	v_mfma_f32_16x16x32_bf16 v[118:121], v[170:173], v[210:213], v[118:121]
	v_mfma_f32_16x16x32_bf16 v[114:117], v[202:205], v[210:213], v[114:117]
	v_mfma_f32_16x16x32_bf16 v[102:105], v[170:173], v[220:223], v[102:105]
	v_mfma_f32_16x16x32_bf16 v[98:101], v[202:205], v[220:223], v[98:101]
	v_mfma_f32_16x16x32_bf16 v[86:89], v[170:173], v[228:231], v[86:89]
	v_mfma_f32_16x16x32_bf16 v[82:85], v[202:205], v[228:231], v[82:85]
	v_mfma_f32_16x16x32_bf16 v[70:73], v[170:173], v[236:239], v[70:73]
	v_mfma_f32_16x16x32_bf16 v[66:69], v[202:205], v[236:239], v[66:69]
	v_mfma_f32_16x16x32_bf16 v[118:121], v[174:177], v[216:219], v[118:121]
	v_mfma_f32_16x16x32_bf16 v[114:117], v[206:209], v[216:219], v[114:117]
	v_mfma_f32_16x16x32_bf16 v[102:105], v[174:177], v[224:227], v[102:105]
	v_mfma_f32_16x16x32_bf16 v[98:101], v[206:209], v[224:227], v[98:101]
	v_mfma_f32_16x16x32_bf16 v[86:89], v[174:177], v[232:235], v[86:89]
	v_mfma_f32_16x16x32_bf16 v[82:85], v[206:209], v[232:235], v[82:85]
	v_mfma_f32_16x16x32_bf16 v[70:73], v[174:177], v[240:243], v[70:73]
	v_mfma_f32_16x16x32_bf16 v[66:69], v[206:209], v[240:243], v[66:69]
	s_setprio 0
	s_barrier
	s_add_i32 s30, s30, s61
	s_mov_b32 m0, s30
	ds_read_b128 v[210:213], v200 offset:16384
	ds_read_b128 v[216:219], v200 offset:17408
	ds_read_b128 v[220:223], v200 offset:18432
	ds_read_b128 v[224:227], v200 offset:19456
	ds_read_b128 v[228:231], v200 offset:20480
	ds_read_b128 v[232:235], v200 offset:21504
	ds_read_b128 v[236:239], v200 offset:22528
	ds_read_b128 v[240:243], v200 offset:23552
	global_load_lds_dwordx4 v154, s[10:11]
	s_add_i32 m0, s30, 0x2000
	s_add_u32 s42, s10, 0x40000
	s_addc_u32 s43, s11, 0
	s_add_i32 s30, s31, s61
	global_load_lds_dwordx4 v158, s[10:11]
	s_mov_b32 m0, s30
	s_nop 0
	global_load_lds_dwordx4 v154, s[42:43]
	s_mov_b32 m0, s59
	s_nop 0
	global_load_lds_dwordx4 v152, s[12:13]
	s_mov_b32 m0, s62
	s_nop 0
	global_load_lds_dwordx4 v156, s[12:13]
	s_waitcnt vmcnt(7)
	s_waitcnt lgkmcnt(0)
	s_barrier
	s_setprio 1
	s_waitcnt lgkmcnt(0)
	v_mfma_f32_16x16x32_bf16 v[62:65], v[130:133], v[210:213], v[62:65]
	v_mfma_f32_16x16x32_bf16 v[58:61], v[138:141], v[210:213], v[58:61]
	v_mfma_f32_16x16x32_bf16 v[46:49], v[130:133], v[220:223], v[46:49]
	v_mfma_f32_16x16x32_bf16 v[42:45], v[138:141], v[220:223], v[42:45]
	v_mfma_f32_16x16x32_bf16 v[30:33], v[130:133], v[228:231], v[30:33]
	v_mfma_f32_16x16x32_bf16 v[26:29], v[138:141], v[228:231], v[26:29]
	v_mfma_f32_16x16x32_bf16 v[14:17], v[130:133], v[236:239], v[14:17]
	v_mfma_f32_16x16x32_bf16 v[10:13], v[138:141], v[236:239], v[10:13]
	v_mfma_f32_16x16x32_bf16 v[62:65], v[134:137], v[216:219], v[62:65]
	v_mfma_f32_16x16x32_bf16 v[58:61], v[142:145], v[216:219], v[58:61]
	v_mfma_f32_16x16x32_bf16 v[46:49], v[134:137], v[224:227], v[46:49]
	v_mfma_f32_16x16x32_bf16 v[42:45], v[142:145], v[224:227], v[42:45]
	v_mfma_f32_16x16x32_bf16 v[30:33], v[134:137], v[232:235], v[30:33]
	v_mfma_f32_16x16x32_bf16 v[26:29], v[142:145], v[232:235], v[26:29]
	v_mfma_f32_16x16x32_bf16 v[14:17], v[134:137], v[240:243], v[14:17]
	v_mfma_f32_16x16x32_bf16 v[10:13], v[142:145], v[240:243], v[10:13]
	s_setprio 0
	s_setprio 1
	v_mfma_f32_16x16x32_bf16 v[54:57], v[170:173], v[210:213], v[54:57]
	v_mfma_f32_16x16x32_bf16 v[50:53], v[202:205], v[210:213], v[50:53]
	v_mfma_f32_16x16x32_bf16 v[38:41], v[170:173], v[220:223], v[38:41]
	v_mfma_f32_16x16x32_bf16 v[34:37], v[202:205], v[220:223], v[34:37]
	v_mfma_f32_16x16x32_bf16 v[22:25], v[170:173], v[228:231], v[22:25]
	v_mfma_f32_16x16x32_bf16 v[18:21], v[202:205], v[228:231], v[18:21]
	v_mfma_f32_16x16x32_bf16 v[6:9], v[170:173], v[236:239], v[6:9]
	v_mfma_f32_16x16x32_bf16 v[2:5], v[202:205], v[236:239], v[2:5]
	v_mfma_f32_16x16x32_bf16 v[54:57], v[174:177], v[216:219], v[54:57]
	v_mfma_f32_16x16x32_bf16 v[50:53], v[206:209], v[216:219], v[50:53]
	v_mfma_f32_16x16x32_bf16 v[38:41], v[174:177], v[224:227], v[38:41]
	v_mfma_f32_16x16x32_bf16 v[34:37], v[206:209], v[224:227], v[34:37]
	v_mfma_f32_16x16x32_bf16 v[22:25], v[174:177], v[232:235], v[22:25]
	v_mfma_f32_16x16x32_bf16 v[18:21], v[206:209], v[232:235], v[18:21]
	v_mfma_f32_16x16x32_bf16 v[6:9], v[174:177], v[240:243], v[6:9]
	v_mfma_f32_16x16x32_bf16 v[2:5], v[206:209], v[240:243], v[2:5]
	s_setprio 0
	s_barrier
	s_add_i32 m0, s30, 0x2000
	s_nop 0
	global_load_lds_dwordx4 v158, s[42:43]
	s_add_i32 s30, 0, 0x18000
	v_add_u32_e32 v0, s30, v197
	s_add_i32 s31, 0, 0x1c000
	ds_read_b128 v[130:133], v0
	ds_read_b128 v[134:137], v0 offset:1024
	ds_read_b128 v[138:141], v0 offset:2048
	ds_read_b128 v[142:145], v0 offset:3072
	v_add_u32_e32 v0, s31, v197
	ds_read_b128 v[170:173], v0
	ds_read_b128 v[174:177], v0 offset:1024
	ds_read_b128 v[202:205], v0 offset:2048
	ds_read_b128 v[206:209], v0 offset:3072
	s_add_u32 s12, s12, 0x40000
	s_addc_u32 s13, s13, 0
	s_mov_b32 m0, s63
	ds_read_b128 v[210:213], v200 offset:32768
	ds_read_b128 v[216:219], v200 offset:33792
	ds_read_b128 v[220:223], v200 offset:34816
	ds_read_b128 v[224:227], v200 offset:35840
	ds_read_b128 v[228:231], v200 offset:36864
	ds_read_b128 v[232:235], v200 offset:37888
	ds_read_b128 v[236:239], v200 offset:38912
	ds_read_b128 v[240:243], v200 offset:39936
	global_load_lds_dwordx4 v152, s[12:13]
	s_mov_b32 m0, s64
	s_nop 0
	global_load_lds_dwordx4 v156, s[12:13]
	s_waitcnt vmcnt(8)
	s_waitcnt lgkmcnt(0)
	s_barrier
	s_setprio 1
	s_waitcnt lgkmcnt(0)
	v_mfma_f32_16x16x32_bf16 v[126:129], v[130:133], v[210:213], v[126:129]
	v_mfma_f32_16x16x32_bf16 v[122:125], v[138:141], v[210:213], v[122:125]
	v_mfma_f32_16x16x32_bf16 v[110:113], v[130:133], v[220:223], v[110:113]
	v_mfma_f32_16x16x32_bf16 v[106:109], v[138:141], v[220:223], v[106:109]
	v_mfma_f32_16x16x32_bf16 v[94:97], v[130:133], v[228:231], v[94:97]
	v_mfma_f32_16x16x32_bf16 v[90:93], v[138:141], v[228:231], v[90:93]
	v_mfma_f32_16x16x32_bf16 v[78:81], v[130:133], v[236:239], v[78:81]
	v_mfma_f32_16x16x32_bf16 v[74:77], v[138:141], v[236:239], v[74:77]
	v_mfma_f32_16x16x32_bf16 v[126:129], v[134:137], v[216:219], v[126:129]
	v_mfma_f32_16x16x32_bf16 v[122:125], v[142:145], v[216:219], v[122:125]
	v_mfma_f32_16x16x32_bf16 v[110:113], v[134:137], v[224:227], v[110:113]
	v_mfma_f32_16x16x32_bf16 v[106:109], v[142:145], v[224:227], v[106:109]
	v_mfma_f32_16x16x32_bf16 v[94:97], v[134:137], v[232:235], v[94:97]
	v_mfma_f32_16x16x32_bf16 v[90:93], v[142:145], v[232:235], v[90:93]
	v_mfma_f32_16x16x32_bf16 v[78:81], v[134:137], v[240:243], v[78:81]
	v_mfma_f32_16x16x32_bf16 v[74:77], v[142:145], v[240:243], v[74:77]
	s_setprio 0
	s_setprio 1
	v_mfma_f32_16x16x32_bf16 v[118:121], v[170:173], v[210:213], v[118:121]
	v_mfma_f32_16x16x32_bf16 v[114:117], v[202:205], v[210:213], v[114:117]
	v_mfma_f32_16x16x32_bf16 v[102:105], v[170:173], v[220:223], v[102:105]
	v_mfma_f32_16x16x32_bf16 v[98:101], v[202:205], v[220:223], v[98:101]
	v_mfma_f32_16x16x32_bf16 v[86:89], v[170:173], v[228:231], v[86:89]
	v_mfma_f32_16x16x32_bf16 v[82:85], v[202:205], v[228:231], v[82:85]
	v_mfma_f32_16x16x32_bf16 v[70:73], v[170:173], v[236:239], v[70:73]
	v_mfma_f32_16x16x32_bf16 v[66:69], v[202:205], v[236:239], v[66:69]
	v_mfma_f32_16x16x32_bf16 v[118:121], v[174:177], v[216:219], v[118:121]
	v_mfma_f32_16x16x32_bf16 v[114:117], v[206:209], v[216:219], v[114:117]
	v_mfma_f32_16x16x32_bf16 v[102:105], v[174:177], v[224:227], v[102:105]
	v_mfma_f32_16x16x32_bf16 v[98:101], v[206:209], v[224:227], v[98:101]
	v_mfma_f32_16x16x32_bf16 v[86:89], v[174:177], v[232:235], v[86:89]
	v_mfma_f32_16x16x32_bf16 v[82:85], v[206:209], v[232:235], v[82:85]
	v_mfma_f32_16x16x32_bf16 v[70:73], v[174:177], v[240:243], v[70:73]
	v_mfma_f32_16x16x32_bf16 v[66:69], v[206:209], v[240:243], v[66:69]
	s_setprio 0
	s_barrier
	s_add_i32 m0, s30, s61
	s_add_u32 s42, s10, 0x80
	s_addc_u32 s43, s11, 0
	ds_read_b128 v[210:213], v200 offset:49152
	ds_read_b128 v[216:219], v200 offset:50176
	ds_read_b128 v[220:223], v200 offset:51200
	ds_read_b128 v[224:227], v200 offset:52224
	ds_read_b128 v[228:231], v200 offset:53248
	ds_read_b128 v[232:235], v200 offset:54272
	ds_read_b128 v[236:239], v200 offset:55296
	ds_read_b128 v[240:243], v200 offset:56320
	global_load_lds_dwordx4 v154, s[42:43]
	s_add_i32 m0, m0, 0x2000
	s_add_u32 s10, s10, 0x40080
	s_addc_u32 s11, s11, 0
	global_load_lds_dwordx4 v158, s[42:43]
	s_add_i32 m0, s31, s61
	s_add_u32 s42, s12, 0xfffc0080
	s_addc_u32 s43, s13, -1
	global_load_lds_dwordx4 v154, s[10:11]
	s_add_i32 m0, m0, 0x2000
	s_nop 0
	global_load_lds_dwordx4 v158, s[10:11]
	s_mov_b32 m0, s66
	s_nop 0
	global_load_lds_dwordx4 v152, s[42:43]
	s_mov_b32 m0, s67
	s_add_i32 s12, s31, s61
	global_load_lds_dwordx4 v156, s[42:43]
	s_add_i32 s29, s29, 2
	s_add_u32 s8, s8, 0x100
	s_addc_u32 s9, s9, 0
	s_add_u32 s27, s27, 0x100
	s_addc_u32 s28, s28, 0
	s_cmp_gt_u32 s29, 13
	s_cbranch_scc1 .Lk1_skip
	s_add_u32 s10, s8, 0xfffc0080
	s_addc_u32 s11, s9, -1
	s_add_i32 s30, 0, 0x10000
	s_cmp_eq_u32 s29, 12
	s_cselect_b32 s13, s3, s11
	s_cselect_b32 s12, s24, s10
	s_cselect_b32 s11, s25, s28
	s_cselect_b32 s10, s26, s27
	s_add_i32 s31, 0, 0x14000
